# v30 + attention interior loops: L2 prefetch (sc1 dword loads, mirroring the real K/V load addresses) of the K and V tiles 4 steps ahead, counted vmcnt waits re-derived (+3)
# baseline (speedup 1.0000x reference)
.LBB0_1038:
	s_or_b64 exec, exec, s[4:5]
	v_and_b32_e32 v0, 0x60, v26
	s_movk_i32 s4, 0x90
	v_lshlrev_b32_e32 v2, 3, v32
	v_mad_u32_u24 v207, v203, s4, 0
	v_mad_u64_u32 v[0:1], s[4:5], v28, s4, v[0:1]
	v_and_or_b32 v0, v2, 8, v0
	v_lshlrev_b32_e32 v1, 6, v203
	v_add_u32_e32 v208, 0, v0
	v_add3_u32 v204, v207, v1, v184
	v_add_u32_e32 v1, 0, v4
	v_add_u32_e32 v205, 0x9800, v208
	s_waitcnt vmcnt(3)
	ds_write_b128 v1, v[8:11] offset:13312
	s_waitcnt vmcnt(2)
	ds_write2_b64 v205, v[16:17], v[18:19] offset0:128 offset1:130
	s_waitcnt lgkmcnt(0)
	s_barrier
	ds_read_b128 v[0:3], v204
	ds_read_b128 v[4:7], v204 offset:32
	ds_read_b128 v[8:11], v204 offset:6656
	ds_read_b128 v[12:15], v204 offset:6688
	ds_read_b128 v[16:19], v204 offset:64
	ds_read_b128 v[28:31], v204 offset:96
	ds_read_b128 v[64:67], v204 offset:6720
	ds_read_b128 v[68:71], v204 offset:6752
	ds_read_b128 v[72:75], v204 offset:128
	ds_read_b128 v[76:79], v204 offset:160
	ds_read_b128 v[80:83], v204 offset:6784
	ds_read_b128 v[84:87], v204 offset:6816
	s_mov_b32 s91, 2
	s_lshl_b32 s87, s6, 2
	s_waitcnt lgkmcnt(11)
	v_mfma_f32_32x32x16_bf16 v[48:63], v[0:3], v[100:103], 0
	s_mov_b32 s79, 0
	s_waitcnt lgkmcnt(9)
	v_mfma_f32_32x32x16_bf16 v[32:47], v[8:11], v[100:103], 0
	v_mfma_f32_32x32x16_bf16 v[48:63], v[4:7], v[104:107], v[48:63]
	s_waitcnt lgkmcnt(8)
	v_mfma_f32_32x32x16_bf16 v[32:47], v[12:15], v[104:107], v[32:47]
	s_waitcnt lgkmcnt(7)
	v_mfma_f32_32x32x16_bf16 v[48:63], v[16:19], v[108:111], v[48:63]
	s_waitcnt lgkmcnt(5)
	v_mfma_f32_32x32x16_bf16 v[32:47], v[64:67], v[108:111], v[32:47]
	v_mfma_f32_32x32x16_bf16 v[48:63], v[28:31], v[112:115], v[48:63]
	s_waitcnt lgkmcnt(4)
	v_mfma_f32_32x32x16_bf16 v[32:47], v[68:71], v[112:115], v[32:47]
	s_waitcnt lgkmcnt(3)
	v_mfma_f32_32x32x16_bf16 v[48:63], v[72:75], v[116:119], v[48:63]
	s_waitcnt lgkmcnt(1)
	v_mfma_f32_32x32x16_bf16 v[32:47], v[80:83], v[116:119], v[32:47]
	v_mfma_f32_32x32x16_bf16 v[48:63], v[76:79], v[120:123], v[48:63]
	s_waitcnt lgkmcnt(0)
	v_mfma_f32_32x32x16_bf16 v[32:47], v[84:87], v[120:123], v[32:47]
	ds_read_b128 v[172:175], v204 offset:13312
	ds_read_b128 v[152:155], v204 offset:13344
	ds_read_b128 v[180:183], v204 offset:19968
	ds_read_b128 v[164:167], v204 offset:20000
	ds_read_b128 v[156:159], v204 offset:13376
	ds_read_b128 v[140:143], v204 offset:13408
	ds_read_b128 v[176:179], v204 offset:20032
	ds_read_b128 v[160:163], v204 offset:20064
	ds_read_b128 v[148:151], v204 offset:13440
	ds_read_b128 v[136:139], v204 offset:13472
	ds_read_b128 v[168:171], v204 offset:20096
	ds_read_b128 v[144:147], v204 offset:20128
	s_add_u32 s4, s60, 0x100
	v_lshl_add_u64 v[0:1], s[60:61], 0, v[24:25]
	v_mov_b32_e32 v27, v97
	s_addc_u32 s5, 0, 0
	v_lshl_add_u64 v[190:191], v[0:1], 0, v[26:27]
	v_lshl_add_u64 v[0:1], s[4:5], 0, v[24:25]
	v_mov_b32_e32 v199, 0
	v_lshl_add_u64 v[188:189], s[96:97], 0, v[20:21]
	v_lshl_add_u64 v[186:187], s[96:97], 0, v[22:23]
	v_lshl_add_u64 v[98:99], v[0:1], 0, v[26:27]
	s_add_u32 s98, s94, 0x12209000
	s_addc_u32 s99, s95, 0
	s_add_u32 s100, s94, 0x11200000
	s_addc_u32 s101, s95, 0

	v_exp_f32_e32 v48, v48
	v_exp_f32_e32 v49, v49
	v_exp_f32_e32 v50, v50
	v_add_f32_e32 v195, v48, v49
	v_exp_f32_e32 v51, v51
	v_add_f32_e32 v195, v50, v195
	v_exp_f32_e32 v52, v52
	v_add_f32_e32 v195, v51, v195
	v_exp_f32_e32 v53, v53
	v_add_f32_e32 v195, v52, v195
	v_exp_f32_e32 v54, v54
	v_add_f32_e32 v195, v53, v195
	v_exp_f32_e32 v55, v55
	v_add_f32_e32 v195, v54, v195
	v_exp_f32_e32 v56, v56
	v_add_f32_e32 v195, v55, v195
	v_exp_f32_e32 v57, v57
	v_add_f32_e32 v195, v56, v195
	v_exp_f32_e32 v58, v58
	v_add_f32_e32 v195, v57, v195
	v_exp_f32_e32 v59, v59
	v_add_f32_e32 v195, v58, v195
	v_exp_f32_e32 v60, v60
	v_add_f32_e32 v195, v59, v195
	v_exp_f32_e32 v61, v61
	v_add_f32_e32 v195, v60, v195
	v_exp_f32_e32 v62, v62
	v_add_f32_e32 v195, v61, v195
	v_exp_f32_e32 v63, v63
	v_add_f32_e32 v195, v62, v195
	v_add_f32_e32 v195, v63, v195
	v_lshl_add_u64 v[242:243], s[98:99], 0, v[188:189]
	v_lshl_add_u64 v[244:245], s[100:101], 0, v[190:191]
	global_load_dword v246, v[242:243], off sc1
	global_load_dword v246, v[242:243], off offset:64 sc1
	global_load_dword v246, v[244:245], off offset:256 sc1

	s_movk_i32 s93, 0xbf
	v_mov_b32_e32 v0, 0
	v_mov_b32_e32 v1, v199
	v_mov_b32_e32 v2, v199
	v_mov_b32_e32 v3, v199
	v_mov_b32_e32 v4, v199
	v_mov_b32_e32 v5, v199
	v_mov_b32_e32 v6, v199
	v_mov_b32_e32 v7, v199
	v_mov_b32_e32 v8, v199
	v_mov_b32_e32 v9, v199
	v_mov_b32_e32 v10, v199
	v_mov_b32_e32 v11, v199
	v_mov_b32_e32 v12, v199
	v_mov_b32_e32 v13, v199
	v_mov_b32_e32 v14, v199
	v_mov_b32_e32 v15, v199
	v_mov_b32_e32 v16, 0
	v_mov_b32_e32 v17, v199
	v_mov_b32_e32 v18, v199
	v_mov_b32_e32 v19, v199
	v_mov_b32_e32 v20, v199
	v_mov_b32_e32 v21, v199
	v_mov_b32_e32 v22, v199
	v_mov_b32_e32 v23, v199
	v_mov_b32_e32 v24, v199
	v_mov_b32_e32 v25, v199
	v_mov_b32_e32 v26, v199
	v_mov_b32_e32 v27, v199
	v_mov_b32_e32 v28, v199
	v_mov_b32_e32 v29, v199
	v_mov_b32_e32 v30, v199
	v_mov_b32_e32 v31, v199
.LBB0_1039:
	s_waitcnt lgkmcnt(11)
	v_mfma_f32_32x32x16_bf16 v[64:79], v[172:175], v[100:103], 0
	v_exp_f32_e32 v32, v32
	v_exp_f32_e32 v33, v33
	v_exp_f32_e32 v34, v34
	s_waitcnt lgkmcnt(9)
	v_mfma_f32_32x32x16_bf16 v[80:95], v[180:183], v[100:103], 0
	v_add_f32_e32 v251, v32, v33
	v_cvt_pk_bf16_f32 v48, v48, v49
	v_exp_f32_e32 v35, v35
	v_add_f32_e32 v251, v34, v251
	v_mfma_f32_32x32x16_bf16 v[64:79], v[152:155], v[104:107], v[64:79]
	v_exp_f32_e32 v36, v36
	v_add_f32_e32 v251, v35, v251
	v_cvt_pk_bf16_f32 v49, v50, v51
	v_exp_f32_e32 v37, v37
	s_waitcnt lgkmcnt(8)
	v_mfma_f32_32x32x16_bf16 v[80:95], v[164:167], v[104:107], v[80:95]
	v_add_f32_e32 v251, v36, v251
	v_exp_f32_e32 v38, v38
	v_add_f32_e32 v251, v37, v251
	v_cvt_pk_bf16_f32 v50, v52, v53
	s_waitcnt lgkmcnt(7)
	v_mfma_f32_32x32x16_bf16 v[64:79], v[156:159], v[108:111], v[64:79]
	v_exp_f32_e32 v39, v39
	v_add_f32_e32 v251, v38, v251
	v_exp_f32_e32 v40, v40
	s_mul_i32 s6, s91, 0x3400
	s_add_i32 s7, s6, 0

	v_add_u32_e32 v253, s7, v96
	s_waitcnt vmcnt(4)
	ds_write_b128 v253, v[128:131]
	s_and_saveexec_b64 s[4:5], s[2:3]
	v_add_u32_e32 v253, s7, v185
	ds_write_b128 v253, v[124:127]
	s_or_b64 exec, exec, s[4:5]
	v_lshl_add_u64 v[200:201], s[100:101], 0, v[190:191]

	v_add_u32_e32 v206, 0xc000, v208
	v_lshl_add_u64 v[128:129], s[98:99], 0, v[188:189]
	s_nop 0
	global_load_dwordx4 v[128:131], v[128:129], off
	s_waitcnt vmcnt(4)
	ds_write2_b64 v206, v[132:133], v[134:135] offset1:2

	s_and_saveexec_b64 s[4:5], s[2:3]
	s_cbranch_execz .LatA_h0
	v_lshl_add_u64 v[124:125], s[98:99], 0, v[186:187]
	s_nop 0
	global_load_dwordx4 v[124:127], v[124:125], off
.LatA_h0:
	s_or_b64 exec, exec, s[4:5]
	global_load_dwordx4 v[132:135], v[200:201], off offset:256

	s_add_u32 s98, s98, 0xc000
	s_addc_u32 s99, s99, 0
	v_lshl_add_u64 v[242:243], s[98:99], 0, v[188:189]
	s_add_u32 s98, s98, 0x2000
	s_addc_u32 s99, s99, 0
	v_lshl_add_u64 v[244:245], s[98:99], 0, v[188:189]
	s_sub_u32 s98, s98, 0xe000
	s_subb_u32 s99, s99, 0
	global_load_dword v246, v[242:243], off sc1
	global_load_dword v246, v[244:245], off sc1
	global_load_dword v246, v[200:201], off offset:768 sc1

	s_waitcnt lgkmcnt(7)
	v_mfma_f32_32x32x16_bf16 v[80:95], v[176:179], v[108:111], v[80:95]
	v_add_f32_e32 v251, v39, v251
	v_cvt_pk_bf16_f32 v51, v54, v55
	v_exp_f32_e32 v41, v41
	v_add_f32_e32 v251, v40, v251
	v_mfma_f32_32x32x16_bf16 v[64:79], v[140:143], v[112:115], v[64:79]
	v_exp_f32_e32 v42, v42
	v_add_f32_e32 v251, v41, v251
	v_cvt_pk_bf16_f32 v52, v56, v57
	v_exp_f32_e32 v43, v43
	s_waitcnt lgkmcnt(6)
	v_mfma_f32_32x32x16_bf16 v[80:95], v[160:163], v[112:115], v[80:95]
	v_add_f32_e32 v251, v42, v251
	v_exp_f32_e32 v44, v44
	v_add_f32_e32 v251, v43, v251
	v_cvt_pk_bf16_f32 v53, v58, v59
	s_waitcnt lgkmcnt(5)
	v_mfma_f32_32x32x16_bf16 v[64:79], v[148:151], v[116:119], v[64:79]
	v_exp_f32_e32 v45, v45
	v_add_f32_e32 v251, v44, v251
	v_exp_f32_e32 v46, v46
	v_add_f32_e32 v251, v45, v251
	v_add_u32_e32 v198, v207, v184
	ds_read_b128 v[210:213], v198 offset:44544
	ds_read_b128 v[214:217], v198 offset:39936
	ds_read_b128 v[218:221], v198 offset:39968
	ds_read_b128 v[222:225], v198 offset:44576
	ds_read_b128 v[226:229], v198 offset:40000
	ds_read_b128 v[230:233], v198 offset:44608
	ds_read_b128 v[234:237], v198 offset:40032
	ds_read_b128 v[238:241], v198 offset:44640
	s_waitcnt lgkmcnt(11)
	v_mfma_f32_32x32x16_bf16 v[80:95], v[168:171], v[116:119], v[80:95]
	v_cvt_pk_bf16_f32 v54, v60, v61
	v_exp_f32_e32 v47, v47
	v_add_f32_e32 v251, v46, v251
	v_add_f32_e32 v251, v47, v251
	v_mfma_f32_32x32x16_bf16 v[64:79], v[136:139], v[120:123], v[64:79]
	v_cvt_pk_bf16_f32 v55, v62, v63
	v_cvt_pk_bf16_f32 v32, v32, v33
	v_cvt_pk_bf16_f32 v33, v34, v35
	v_cvt_pk_bf16_f32 v34, v36, v37
	v_cvt_pk_bf16_f32 v35, v38, v39
	v_cvt_pk_bf16_f32 v36, v40, v41
	s_waitcnt lgkmcnt(10)
	v_mfma_f32_32x32x16_bf16 v[80:95], v[144:147], v[120:123], v[80:95]
	v_cvt_pk_bf16_f32 v37, v42, v43
	v_cvt_pk_bf16_f32 v38, v44, v45
	v_cvt_pk_bf16_f32 v39, v46, v47
	v_add_f32_e32 v195, v195, v251
	v_add_f32_e32 v199, v199, v195
	s_waitcnt lgkmcnt(0)
	s_barrier

	v_add_u32_e32 v197, s6, v204
	s_setprio 1
	v_mfma_f32_32x32x16_bf16 v[0:15], v[48:51], v[210:213], v[0:15]
	ds_read_b128 v[172:175], v197
	ds_read_b128 v[152:155], v197 offset:32
	v_mfma_f32_32x32x16_bf16 v[0:15], v[52:55], v[222:225], v[0:15]
	ds_read_b128 v[180:183], v197 offset:6656
	ds_read_b128 v[164:167], v197 offset:6688
	v_mfma_f32_32x32x16_bf16 v[0:15], v[32:35], v[230:233], v[0:15]
	ds_read_b128 v[156:159], v197 offset:64
	ds_read_b128 v[140:143], v197 offset:96
	v_exp_f32_e32 v64, v64
	v_exp_f32_e32 v65, v65
	v_exp_f32_e32 v66, v66
	v_add_f32_e32 v195, v64, v65
	v_mfma_f32_32x32x16_bf16 v[0:15], v[36:39], v[238:241], v[0:15]
	s_setprio 0
	ds_read_b128 v[176:179], v197 offset:6720
	ds_read_b128 v[160:163], v197 offset:6752
	v_exp_f32_e32 v67, v67
	v_add_f32_e32 v195, v66, v195
	v_exp_f32_e32 v68, v68
	v_add_f32_e32 v195, v67, v195
	v_exp_f32_e32 v69, v69
	v_add_f32_e32 v195, v68, v195
	v_mfma_f32_32x32x16_bf16 v[16:31], v[48:51], v[214:217], v[16:31]
	ds_read_b128 v[148:151], v197 offset:128
	ds_read_b128 v[136:139], v197 offset:160
	v_exp_f32_e32 v70, v70
	v_add_f32_e32 v195, v69, v195
	v_exp_f32_e32 v71, v71
	v_add_f32_e32 v195, v70, v195
	v_exp_f32_e32 v72, v72
	v_mfma_f32_32x32x16_bf16 v[16:31], v[52:55], v[218:221], v[16:31]
	ds_read_b128 v[168:171], v197 offset:6784
	ds_read_b128 v[144:147], v197 offset:6816
	v_add_f32_e32 v195, v71, v195
	v_exp_f32_e32 v73, v73
	v_add_f32_e32 v195, v72, v195
	v_exp_f32_e32 v74, v74
	v_add_f32_e32 v195, v73, v195
	v_mfma_f32_32x32x16_bf16 v[16:31], v[32:35], v[226:229], v[16:31]
	v_exp_f32_e32 v75, v75
	v_add_f32_e32 v195, v74, v195
	v_exp_f32_e32 v76, v76
	v_add_f32_e32 v195, v75, v195
	v_exp_f32_e32 v77, v77
	v_mfma_f32_32x32x16_bf16 v[16:31], v[36:39], v[234:237], v[16:31]
	v_add_f32_e32 v195, v76, v195
	v_exp_f32_e32 v78, v78
	v_add_f32_e32 v195, v77, v195
	v_exp_f32_e32 v79, v79
	v_add_f32_e32 v195, v78, v195
	v_add_f32_e32 v195, v79, v195
	s_waitcnt lgkmcnt(11)
	v_mfma_f32_32x32x16_bf16 v[48:63], v[172:175], v[100:103], 0
	v_exp_f32_e32 v80, v80
	v_exp_f32_e32 v81, v81
	v_exp_f32_e32 v82, v82
	s_waitcnt lgkmcnt(9)
	v_mfma_f32_32x32x16_bf16 v[32:47], v[180:183], v[100:103], 0
	v_add_f32_e32 v251, v80, v81
	v_cvt_pk_bf16_f32 v64, v64, v65
	v_exp_f32_e32 v83, v83
	v_add_f32_e32 v251, v82, v251
	v_mfma_f32_32x32x16_bf16 v[48:63], v[152:155], v[104:107], v[48:63]
	v_exp_f32_e32 v84, v84
	v_add_f32_e32 v251, v83, v251
	v_cvt_pk_bf16_f32 v65, v66, v67
	v_exp_f32_e32 v85, v85
	s_waitcnt lgkmcnt(8)
	v_mfma_f32_32x32x16_bf16 v[32:47], v[164:167], v[104:107], v[32:47]
	v_add_f32_e32 v251, v84, v251
	v_exp_f32_e32 v86, v86
	v_add_f32_e32 v251, v85, v251
	v_cvt_pk_bf16_f32 v66, v68, v69
	s_waitcnt lgkmcnt(7)
	v_mfma_f32_32x32x16_bf16 v[48:63], v[156:159], v[108:111], v[48:63]
	v_exp_f32_e32 v87, v87
	v_add_f32_e32 v251, v86, v251
	v_exp_f32_e32 v88, v88
	s_add_i32 s4, s91, 1
	s_cmp_lg_u32 s91, 2
	s_cselect_b32 s74, s4, 0
	s_mul_i32 s6, s74, 0x3400
	s_add_i32 s7, s6, 0
	s_add_u32 s98, s98, 0x3000
	s_addc_u32 s99, s99, 0

	v_add_u32_e32 v253, s7, v96
	s_waitcnt vmcnt(4)
	ds_write_b128 v253, v[128:131]
	s_and_saveexec_b64 s[4:5], s[2:3]
	v_add_u32_e32 v253, s7, v185
	ds_write_b128 v253, v[124:127]
	s_or_b64 exec, exec, s[4:5]
	v_lshl_add_u64 v[200:201], s[100:101], 0, v[190:191]

	s_waitcnt vmcnt(3)
	ds_write2_b64 v205, v[132:133], v[134:135] offset0:128 offset1:130
	v_lshl_add_u64 v[128:129], s[98:99], 0, v[188:189]
	s_nop 0
	global_load_dwordx4 v[128:131], v[128:129], off

	s_and_saveexec_b64 s[4:5], s[2:3]
	s_cbranch_execz .LatA_h1
	v_lshl_add_u64 v[124:125], s[98:99], 0, v[186:187]
	s_nop 0
	global_load_dwordx4 v[124:127], v[124:125], off
.LatA_h1:
	s_or_b64 exec, exec, s[4:5]
	global_load_dwordx4 v[132:135], v[200:201], off offset:384

	s_add_u32 s98, s98, 0xc000
	s_addc_u32 s99, s99, 0
	v_lshl_add_u64 v[242:243], s[98:99], 0, v[188:189]
	s_add_u32 s98, s98, 0x2000
	s_addc_u32 s99, s99, 0
	v_lshl_add_u64 v[244:245], s[98:99], 0, v[188:189]
	s_sub_u32 s98, s98, 0xe000
	s_subb_u32 s99, s99, 0
	global_load_dword v246, v[242:243], off sc1
	global_load_dword v246, v[244:245], off sc1
	global_load_dword v246, v[200:201], off offset:896 sc1

	s_sub_u32 s98, s98, 0x3000
	s_subb_u32 s99, s99, 0

	s_waitcnt lgkmcnt(7)
	v_mfma_f32_32x32x16_bf16 v[32:47], v[176:179], v[108:111], v[32:47]
	v_add_f32_e32 v251, v87, v251
	v_cvt_pk_bf16_f32 v67, v70, v71
	v_exp_f32_e32 v89, v89
	v_add_f32_e32 v251, v88, v251
	v_mfma_f32_32x32x16_bf16 v[48:63], v[140:143], v[112:115], v[48:63]
	v_exp_f32_e32 v90, v90
	v_add_f32_e32 v251, v89, v251
	v_cvt_pk_bf16_f32 v68, v72, v73
	v_exp_f32_e32 v91, v91
	s_waitcnt lgkmcnt(6)
	v_mfma_f32_32x32x16_bf16 v[32:47], v[160:163], v[112:115], v[32:47]
	v_add_f32_e32 v251, v90, v251
	v_exp_f32_e32 v92, v92
	v_add_f32_e32 v251, v91, v251
	v_cvt_pk_bf16_f32 v69, v74, v75
	s_waitcnt lgkmcnt(5)
	v_mfma_f32_32x32x16_bf16 v[48:63], v[148:151], v[116:119], v[48:63]
	v_exp_f32_e32 v93, v93
	v_add_f32_e32 v251, v92, v251
	v_exp_f32_e32 v94, v94
	v_add_f32_e32 v251, v93, v251
	v_add_u32_e32 v198, v207, v184
	ds_read_b128 v[210:213], v198 offset:53760
	ds_read_b128 v[214:217], v198 offset:49152
	ds_read_b128 v[218:221], v198 offset:49184
	ds_read_b128 v[222:225], v198 offset:53792
	ds_read_b128 v[226:229], v198 offset:49216
	ds_read_b128 v[230:233], v198 offset:53824
	ds_read_b128 v[234:237], v198 offset:49248
	ds_read_b128 v[238:241], v198 offset:53856
	s_waitcnt lgkmcnt(11)
	v_mfma_f32_32x32x16_bf16 v[32:47], v[168:171], v[116:119], v[32:47]
	v_cvt_pk_bf16_f32 v70, v76, v77
	v_exp_f32_e32 v95, v95
	v_add_f32_e32 v251, v94, v251
	v_add_f32_e32 v251, v95, v251
	v_mfma_f32_32x32x16_bf16 v[48:63], v[136:139], v[120:123], v[48:63]
	v_cvt_pk_bf16_f32 v71, v78, v79
	v_cvt_pk_bf16_f32 v80, v80, v81
	v_cvt_pk_bf16_f32 v81, v82, v83
	v_cvt_pk_bf16_f32 v82, v84, v85
	v_cvt_pk_bf16_f32 v83, v86, v87
	v_cvt_pk_bf16_f32 v84, v88, v89
	s_waitcnt lgkmcnt(10)
	v_mfma_f32_32x32x16_bf16 v[32:47], v[144:147], v[120:123], v[32:47]
	v_cvt_pk_bf16_f32 v85, v90, v91
	v_cvt_pk_bf16_f32 v86, v92, v93
	v_cvt_pk_bf16_f32 v87, v94, v95
	v_add_f32_e32 v195, v195, v251
	v_add_f32_e32 v199, v199, v195
	s_add_i32 s92, s79, 2
	s_waitcnt lgkmcnt(0)
	s_barrier

	s_cmp_ge_u32 s92, s87
	s_cbranch_scc1 .LatA_yplain

	v_add_u32_e32 v197, s6, v204
	s_setprio 1
	v_mfma_f32_32x32x16_bf16 v[0:15], v[64:67], v[210:213], v[0:15]
	ds_read_b128 v[172:175], v197
	ds_read_b128 v[152:155], v197 offset:32
	v_mfma_f32_32x32x16_bf16 v[0:15], v[68:71], v[222:225], v[0:15]
	ds_read_b128 v[180:183], v197 offset:6656
	ds_read_b128 v[164:167], v197 offset:6688
	v_mfma_f32_32x32x16_bf16 v[0:15], v[80:83], v[230:233], v[0:15]
	ds_read_b128 v[156:159], v197 offset:64
	ds_read_b128 v[140:143], v197 offset:96
	v_exp_f32_e32 v48, v48
	v_exp_f32_e32 v49, v49
	v_exp_f32_e32 v50, v50
	v_add_f32_e32 v195, v48, v49
	v_mfma_f32_32x32x16_bf16 v[0:15], v[84:87], v[238:241], v[0:15]
	s_setprio 0
	ds_read_b128 v[176:179], v197 offset:6720
	ds_read_b128 v[160:163], v197 offset:6752
	v_exp_f32_e32 v51, v51
	v_add_f32_e32 v195, v50, v195
	v_exp_f32_e32 v52, v52
	v_add_f32_e32 v195, v51, v195
	v_exp_f32_e32 v53, v53
	v_add_f32_e32 v195, v52, v195
	v_mfma_f32_32x32x16_bf16 v[16:31], v[64:67], v[214:217], v[16:31]
	ds_read_b128 v[148:151], v197 offset:128
	ds_read_b128 v[136:139], v197 offset:160
	v_exp_f32_e32 v54, v54
	v_add_f32_e32 v195, v53, v195
	v_exp_f32_e32 v55, v55
	v_add_f32_e32 v195, v54, v195
	v_exp_f32_e32 v56, v56
	v_mfma_f32_32x32x16_bf16 v[16:31], v[68:71], v[218:221], v[16:31]
	ds_read_b128 v[168:171], v197 offset:6784
	ds_read_b128 v[144:147], v197 offset:6816
	v_add_f32_e32 v195, v55, v195
	v_exp_f32_e32 v57, v57
	v_add_f32_e32 v195, v56, v195
	v_exp_f32_e32 v58, v58
	v_add_f32_e32 v195, v57, v195
	v_mfma_f32_32x32x16_bf16 v[16:31], v[80:83], v[226:229], v[16:31]
	v_exp_f32_e32 v59, v59
	v_add_f32_e32 v195, v58, v195
	v_exp_f32_e32 v60, v60
	v_add_f32_e32 v195, v59, v195
	v_exp_f32_e32 v61, v61
	v_mfma_f32_32x32x16_bf16 v[16:31], v[84:87], v[234:237], v[16:31]
	v_add_f32_e32 v195, v60, v195
	v_exp_f32_e32 v62, v62
	v_add_f32_e32 v195, v61, v195
	v_exp_f32_e32 v63, v63
	v_add_f32_e32 v195, v62, v195
	v_add_f32_e32 v195, v63, v195
	s_branch .LatA_ctl

.LBB0_1103:
	s_or_b64 exec, exec, s[4:5]
	v_and_b32_e32 v2, 0x60, v190
	s_movk_i32 s4, 0x90
	v_lshlrev_b32_e32 v1, 3, v24
	v_mad_u32_u24 v208, v207, s4, 0
	v_mad_u64_u32 v[2:3], s[4:5], v20, s4, v[2:3]
	v_and_or_b32 v1, v1, 8, v2
	v_lshlrev_b32_e32 v2, 6, v207
	v_add_u32_e32 v210, 0, v1
	v_add3_u32 v209, v208, v2, v184
	v_add_u32_e32 v0, 0, v0
	v_add_u32_e32 v211, 0x9800, v210
	s_waitcnt vmcnt(3)
	ds_write_b128 v0, v[4:7] offset:13312
	s_waitcnt vmcnt(2)
	ds_write2_b64 v211, v[8:9], v[10:11] offset0:128 offset1:130
	s_waitcnt lgkmcnt(0)
	s_barrier
	ds_read_b128 v[0:3], v209
	ds_read_b128 v[4:7], v209 offset:32
	ds_read_b128 v[8:11], v209 offset:6656
	ds_read_b128 v[12:15], v209 offset:6688
	ds_read_b128 v[16:19], v209 offset:64
	ds_read_b128 v[20:23], v209 offset:96
	ds_read_b128 v[24:27], v209 offset:6720
	ds_read_b128 v[28:31], v209 offset:6752
	ds_read_b128 v[64:67], v209 offset:128
	ds_read_b128 v[68:71], v209 offset:160
	ds_read_b128 v[72:75], v209 offset:6784
	ds_read_b128 v[76:79], v209 offset:6816
	s_mov_b32 s90, 2
	s_lshl_b32 s69, s68, 2
	s_mov_b32 s40, 0
	s_cmp_eq_u32 s68, 0
	s_waitcnt lgkmcnt(11)
	v_mfma_f32_32x32x16_bf16 v[48:63], v[0:3], v[100:103], 0
	s_waitcnt lgkmcnt(9)
	v_mfma_f32_32x32x16_bf16 v[32:47], v[8:11], v[100:103], 0
	v_mfma_f32_32x32x16_bf16 v[48:63], v[4:7], v[104:107], v[48:63]
	s_waitcnt lgkmcnt(8)
	v_mfma_f32_32x32x16_bf16 v[32:47], v[12:15], v[104:107], v[32:47]
	s_waitcnt lgkmcnt(7)
	v_mfma_f32_32x32x16_bf16 v[48:63], v[16:19], v[108:111], v[48:63]
	s_waitcnt lgkmcnt(5)
	v_mfma_f32_32x32x16_bf16 v[32:47], v[24:27], v[108:111], v[32:47]
	v_mfma_f32_32x32x16_bf16 v[48:63], v[20:23], v[112:115], v[48:63]
	s_waitcnt lgkmcnt(4)
	v_mfma_f32_32x32x16_bf16 v[32:47], v[28:31], v[112:115], v[32:47]
	s_waitcnt lgkmcnt(3)
	v_mfma_f32_32x32x16_bf16 v[48:63], v[64:67], v[116:119], v[48:63]
	s_waitcnt lgkmcnt(1)
	v_mfma_f32_32x32x16_bf16 v[32:47], v[72:75], v[116:119], v[32:47]
	v_mfma_f32_32x32x16_bf16 v[48:63], v[68:71], v[120:123], v[48:63]
	s_waitcnt lgkmcnt(0)
	v_mfma_f32_32x32x16_bf16 v[32:47], v[76:79], v[120:123], v[32:47]
	s_cbranch_scc1 .LBB0_1114
	ds_read_b128 v[172:175], v209 offset:13312
	ds_read_b128 v[152:155], v209 offset:13344
	ds_read_b128 v[180:183], v209 offset:19968
	ds_read_b128 v[164:167], v209 offset:20000
	ds_read_b128 v[156:159], v209 offset:13376
	ds_read_b128 v[140:143], v209 offset:13408
	ds_read_b128 v[176:179], v209 offset:20032
	ds_read_b128 v[160:163], v209 offset:20064
	ds_read_b128 v[148:151], v209 offset:13440
	ds_read_b128 v[136:139], v209 offset:13472
	ds_read_b128 v[168:171], v209 offset:20096
	ds_read_b128 v[144:147], v209 offset:20128
	v_lshl_add_u64 v[0:1], s[60:61], 0, v[192:193]
	v_mov_b32_e32 v191, v97
	v_mov_b32_e32 v198, 0
	v_lshl_add_u64 v[98:99], s[96:97], 0, v[186:187]
	v_lshl_add_u64 v[202:203], s[96:97], 0, v[188:189]
	v_lshl_add_u64 v[204:205], v[0:1], 0, v[190:191]
	s_add_u32 s98, s94, 0x12209000
	s_addc_u32 s99, s95, 0
	s_add_u32 s100, s94, 0x11200000
	s_addc_u32 s101, s95, 0

	v_exp_f32_e32 v48, v48
	v_exp_f32_e32 v49, v49
	v_exp_f32_e32 v50, v50
	v_add_f32_e32 v195, v48, v49
	v_exp_f32_e32 v51, v51
	v_add_f32_e32 v195, v50, v195
	v_exp_f32_e32 v52, v52
	v_add_f32_e32 v195, v51, v195
	v_exp_f32_e32 v53, v53
	v_add_f32_e32 v195, v52, v195
	v_exp_f32_e32 v54, v54
	v_add_f32_e32 v195, v53, v195
	v_exp_f32_e32 v55, v55
	v_add_f32_e32 v195, v54, v195
	v_exp_f32_e32 v56, v56
	v_add_f32_e32 v195, v55, v195
	v_exp_f32_e32 v57, v57
	v_add_f32_e32 v195, v56, v195
	v_exp_f32_e32 v58, v58
	v_add_f32_e32 v195, v57, v195
	v_exp_f32_e32 v59, v59
	v_add_f32_e32 v195, v58, v195
	v_exp_f32_e32 v60, v60
	v_add_f32_e32 v195, v59, v195
	v_exp_f32_e32 v61, v61
	v_add_f32_e32 v195, v60, v195
	v_exp_f32_e32 v62, v62
	v_add_f32_e32 v195, v61, v195
	v_exp_f32_e32 v63, v63
	v_add_f32_e32 v195, v62, v195
	v_add_f32_e32 v195, v63, v195
	v_lshl_add_u64 v[242:243], s[98:99], 0, v[98:99]
	v_lshl_add_u64 v[244:245], s[100:101], 0, v[204:205]
	global_load_dword v246, v[242:243], off sc1
	global_load_dword v246, v[242:243], off offset:64 sc1
	global_load_dword v246, v[244:245], off offset:256 sc1

	v_mov_b32_e32 v0, 0
	v_mov_b32_e32 v1, v198
	v_mov_b32_e32 v2, v198
	v_mov_b32_e32 v3, v198
	v_mov_b32_e32 v4, v198
	v_mov_b32_e32 v5, v198
	v_mov_b32_e32 v6, v198
	v_mov_b32_e32 v7, v198
	v_mov_b32_e32 v8, v198
	v_mov_b32_e32 v9, v198
	v_mov_b32_e32 v10, v198
	v_mov_b32_e32 v11, v198
	v_mov_b32_e32 v12, v198
	v_mov_b32_e32 v13, v198
	v_mov_b32_e32 v14, v198
	v_mov_b32_e32 v15, v198
	v_mov_b32_e32 v16, 0
	v_mov_b32_e32 v17, v198
	v_mov_b32_e32 v18, v198
	v_mov_b32_e32 v19, v198
	v_mov_b32_e32 v20, v198
	v_mov_b32_e32 v21, v198
	v_mov_b32_e32 v22, v198
	v_mov_b32_e32 v23, v198
	v_mov_b32_e32 v24, v198
	v_mov_b32_e32 v25, v198
	v_mov_b32_e32 v26, v198
	v_mov_b32_e32 v27, v198
	v_mov_b32_e32 v28, v198
	v_mov_b32_e32 v29, v198
	v_mov_b32_e32 v30, v198
	v_mov_b32_e32 v31, v198
	s_mov_b32 s41, 0x2c000
	s_branch .LBB0_1106
.LBB0_1106:
	s_waitcnt lgkmcnt(11)
	v_mfma_f32_32x32x16_bf16 v[64:79], v[172:175], v[100:103], 0
	v_exp_f32_e32 v32, v32
	v_exp_f32_e32 v33, v33
	v_exp_f32_e32 v34, v34
	s_waitcnt lgkmcnt(9)
	v_mfma_f32_32x32x16_bf16 v[80:95], v[180:183], v[100:103], 0
	v_add_f32_e32 v251, v32, v33
	v_cvt_pk_bf16_f32 v48, v48, v49
	v_exp_f32_e32 v35, v35
	v_add_f32_e32 v251, v34, v251
	v_mfma_f32_32x32x16_bf16 v[64:79], v[152:155], v[104:107], v[64:79]
	v_exp_f32_e32 v36, v36
	v_add_f32_e32 v251, v35, v251
	v_cvt_pk_bf16_f32 v49, v50, v51
	v_exp_f32_e32 v37, v37
	s_waitcnt lgkmcnt(8)
	v_mfma_f32_32x32x16_bf16 v[80:95], v[164:167], v[104:107], v[80:95]
	v_add_f32_e32 v251, v36, v251
	v_exp_f32_e32 v38, v38
	v_add_f32_e32 v251, v37, v251
	v_cvt_pk_bf16_f32 v50, v52, v53
	s_waitcnt lgkmcnt(7)
	v_mfma_f32_32x32x16_bf16 v[64:79], v[156:159], v[108:111], v[64:79]
	v_exp_f32_e32 v39, v39
	v_add_f32_e32 v251, v38, v251
	v_exp_f32_e32 v40, v40
	s_mul_i32 s6, s90, 0x3400
	s_add_i32 s7, s6, 0

	v_add_u32_e32 v253, s7, v96
	s_waitcnt vmcnt(4)
	ds_write_b128 v253, v[128:131]
	s_and_saveexec_b64 s[4:5], s[2:3]
	v_add_u32_e32 v253, s7, v185
	ds_write_b128 v253, v[124:127]
	s_or_b64 exec, exec, s[4:5]
	v_lshl_add_u64 v[200:201], s[100:101], 0, v[204:205]

	v_add_u32_e32 v254, 0xc000, v210
	v_lshl_add_u64 v[128:129], s[98:99], 0, v[98:99]
	s_nop 0
	global_load_dwordx4 v[128:131], v[128:129], off
	s_waitcnt vmcnt(4)
	ds_write2_b64 v254, v[132:133], v[134:135] offset1:2

	s_and_saveexec_b64 s[4:5], s[2:3]
	s_cbranch_execz .LatB_h0
	v_lshl_add_u64 v[124:125], s[98:99], 0, v[202:203]
	s_nop 0
	global_load_dwordx4 v[124:127], v[124:125], off
.LatB_h0:
	s_or_b64 exec, exec, s[4:5]
	global_load_dwordx4 v[132:135], v[200:201], off offset:256

	s_add_u32 s98, s98, 0xc000
	s_addc_u32 s99, s99, 0
	v_lshl_add_u64 v[242:243], s[98:99], 0, v[98:99]
	s_add_u32 s98, s98, 0x2000
	s_addc_u32 s99, s99, 0
	v_lshl_add_u64 v[244:245], s[98:99], 0, v[98:99]
	s_sub_u32 s98, s98, 0xe000
	s_subb_u32 s99, s99, 0
	global_load_dword v246, v[242:243], off sc1
	global_load_dword v246, v[244:245], off sc1
	global_load_dword v246, v[200:201], off offset:768 sc1

	s_waitcnt lgkmcnt(7)
	v_mfma_f32_32x32x16_bf16 v[80:95], v[176:179], v[108:111], v[80:95]
	v_add_f32_e32 v251, v39, v251
	v_cvt_pk_bf16_f32 v51, v54, v55
	v_exp_f32_e32 v41, v41
	v_add_f32_e32 v251, v40, v251
	v_mfma_f32_32x32x16_bf16 v[64:79], v[140:143], v[112:115], v[64:79]
	v_exp_f32_e32 v42, v42
	v_add_f32_e32 v251, v41, v251
	v_cvt_pk_bf16_f32 v52, v56, v57
	v_exp_f32_e32 v43, v43
	s_waitcnt lgkmcnt(6)
	v_mfma_f32_32x32x16_bf16 v[80:95], v[160:163], v[112:115], v[80:95]
	v_add_f32_e32 v251, v42, v251
	v_exp_f32_e32 v44, v44
	v_add_f32_e32 v251, v43, v251
	v_cvt_pk_bf16_f32 v53, v58, v59
	s_waitcnt lgkmcnt(5)
	v_mfma_f32_32x32x16_bf16 v[64:79], v[148:151], v[116:119], v[64:79]
	v_exp_f32_e32 v45, v45
	v_add_f32_e32 v251, v44, v251
	v_exp_f32_e32 v46, v46
	v_add_f32_e32 v251, v45, v251
	v_add_u32_e32 v196, v208, v184
	ds_read_b128 v[212:215], v196 offset:44544
	ds_read_b128 v[216:219], v196 offset:39936
	ds_read_b128 v[220:223], v196 offset:39968
	ds_read_b128 v[224:227], v196 offset:44576
	ds_read_b128 v[228:231], v196 offset:40000
	ds_read_b128 v[232:235], v196 offset:44608
	ds_read_b128 v[236:239], v196 offset:40032
	ds_read_b128 v[240:243], v196 offset:44640
	s_waitcnt lgkmcnt(11)
	v_mfma_f32_32x32x16_bf16 v[80:95], v[168:171], v[116:119], v[80:95]
	v_cvt_pk_bf16_f32 v54, v60, v61
	v_exp_f32_e32 v47, v47
	v_add_f32_e32 v251, v46, v251
	v_add_f32_e32 v251, v47, v251
	v_mfma_f32_32x32x16_bf16 v[64:79], v[136:139], v[120:123], v[64:79]
	v_cvt_pk_bf16_f32 v55, v62, v63
	v_cvt_pk_bf16_f32 v32, v32, v33
	v_cvt_pk_bf16_f32 v33, v34, v35
	v_cvt_pk_bf16_f32 v34, v36, v37
	v_cvt_pk_bf16_f32 v35, v38, v39
	v_cvt_pk_bf16_f32 v36, v40, v41
	s_waitcnt lgkmcnt(10)
	v_mfma_f32_32x32x16_bf16 v[80:95], v[144:147], v[120:123], v[80:95]
	v_cvt_pk_bf16_f32 v37, v42, v43
	v_cvt_pk_bf16_f32 v38, v44, v45
	v_cvt_pk_bf16_f32 v39, v46, v47
	v_add_f32_e32 v195, v195, v251
	v_add_f32_e32 v198, v198, v195
	s_waitcnt lgkmcnt(0)
	s_barrier

	v_add_u32_e32 v197, s6, v209
	s_setprio 1
	v_mfma_f32_32x32x16_bf16 v[0:15], v[48:51], v[212:215], v[0:15]
	ds_read_b128 v[172:175], v197
	ds_read_b128 v[152:155], v197 offset:32
	v_mfma_f32_32x32x16_bf16 v[0:15], v[52:55], v[224:227], v[0:15]
	ds_read_b128 v[180:183], v197 offset:6656
	ds_read_b128 v[164:167], v197 offset:6688
	v_mfma_f32_32x32x16_bf16 v[0:15], v[32:35], v[232:235], v[0:15]
	ds_read_b128 v[156:159], v197 offset:64
	ds_read_b128 v[140:143], v197 offset:96
	v_exp_f32_e32 v64, v64
	v_exp_f32_e32 v65, v65
	v_exp_f32_e32 v66, v66
	v_add_f32_e32 v195, v64, v65
	v_mfma_f32_32x32x16_bf16 v[0:15], v[36:39], v[240:243], v[0:15]
	s_setprio 0
	ds_read_b128 v[176:179], v197 offset:6720
	ds_read_b128 v[160:163], v197 offset:6752
	v_exp_f32_e32 v67, v67
	v_add_f32_e32 v195, v66, v195
	v_exp_f32_e32 v68, v68
	v_add_f32_e32 v195, v67, v195
	v_exp_f32_e32 v69, v69
	v_add_f32_e32 v195, v68, v195
	v_mfma_f32_32x32x16_bf16 v[16:31], v[48:51], v[216:219], v[16:31]
	ds_read_b128 v[148:151], v197 offset:128
	ds_read_b128 v[136:139], v197 offset:160
	v_exp_f32_e32 v70, v70
	v_add_f32_e32 v195, v69, v195
	v_exp_f32_e32 v71, v71
	v_add_f32_e32 v195, v70, v195
	v_exp_f32_e32 v72, v72
	v_mfma_f32_32x32x16_bf16 v[16:31], v[52:55], v[220:223], v[16:31]
	ds_read_b128 v[168:171], v197 offset:6784
	ds_read_b128 v[144:147], v197 offset:6816
	v_add_f32_e32 v195, v71, v195
	v_exp_f32_e32 v73, v73
	v_add_f32_e32 v195, v72, v195
	v_exp_f32_e32 v74, v74
	v_add_f32_e32 v195, v73, v195
	v_mfma_f32_32x32x16_bf16 v[16:31], v[32:35], v[228:231], v[16:31]
	v_exp_f32_e32 v75, v75
	v_add_f32_e32 v195, v74, v195
	v_exp_f32_e32 v76, v76
	v_add_f32_e32 v195, v75, v195
	v_exp_f32_e32 v77, v77
	v_mfma_f32_32x32x16_bf16 v[16:31], v[36:39], v[236:239], v[16:31]
	v_add_f32_e32 v195, v76, v195
	v_exp_f32_e32 v78, v78
	v_add_f32_e32 v195, v77, v195
	v_exp_f32_e32 v79, v79
	v_add_f32_e32 v195, v78, v195
	v_add_f32_e32 v195, v79, v195
	s_waitcnt lgkmcnt(11)
	v_mfma_f32_32x32x16_bf16 v[48:63], v[172:175], v[100:103], 0
	v_exp_f32_e32 v80, v80
	v_exp_f32_e32 v81, v81
	v_exp_f32_e32 v82, v82
	s_waitcnt lgkmcnt(9)
	v_mfma_f32_32x32x16_bf16 v[32:47], v[180:183], v[100:103], 0
	v_add_f32_e32 v251, v80, v81
	v_cvt_pk_bf16_f32 v64, v64, v65
	v_exp_f32_e32 v83, v83
	v_add_f32_e32 v251, v82, v251
	v_mfma_f32_32x32x16_bf16 v[48:63], v[152:155], v[104:107], v[48:63]
	v_exp_f32_e32 v84, v84
	v_add_f32_e32 v251, v83, v251
	v_cvt_pk_bf16_f32 v65, v66, v67
	v_exp_f32_e32 v85, v85
	s_waitcnt lgkmcnt(8)
	v_mfma_f32_32x32x16_bf16 v[32:47], v[164:167], v[104:107], v[32:47]
	v_add_f32_e32 v251, v84, v251
	v_exp_f32_e32 v86, v86
	v_add_f32_e32 v251, v85, v251
	v_cvt_pk_bf16_f32 v66, v68, v69
	s_waitcnt lgkmcnt(7)
	v_mfma_f32_32x32x16_bf16 v[48:63], v[156:159], v[108:111], v[48:63]
	v_exp_f32_e32 v87, v87
	v_add_f32_e32 v251, v86, v251
	v_exp_f32_e32 v88, v88
	s_add_i32 s4, s90, 1
	s_cmp_lg_u32 s90, 2
	s_cselect_b32 s68, s4, 0
	s_mul_i32 s6, s68, 0x3400
	s_add_i32 s7, s6, 0
	s_add_u32 s98, s98, 0x3000
	s_addc_u32 s99, s99, 0

	v_add_u32_e32 v253, s7, v96
	s_waitcnt vmcnt(4)
	ds_write_b128 v253, v[128:131]
	s_and_saveexec_b64 s[4:5], s[2:3]
	v_add_u32_e32 v253, s7, v185
	ds_write_b128 v253, v[124:127]
	s_or_b64 exec, exec, s[4:5]
	v_lshl_add_u64 v[200:201], s[100:101], 0, v[204:205]

	s_waitcnt vmcnt(3)
	ds_write2_b64 v211, v[132:133], v[134:135] offset0:128 offset1:130
	v_lshl_add_u64 v[128:129], s[98:99], 0, v[98:99]
	s_nop 0
	global_load_dwordx4 v[128:131], v[128:129], off

	s_and_saveexec_b64 s[4:5], s[2:3]
	s_cbranch_execz .LatB_h1
	v_lshl_add_u64 v[124:125], s[98:99], 0, v[202:203]
	s_nop 0
	global_load_dwordx4 v[124:127], v[124:125], off
.LatB_h1:
	s_or_b64 exec, exec, s[4:5]
	global_load_dwordx4 v[132:135], v[200:201], off offset:384

	s_add_u32 s98, s98, 0xc000
	s_addc_u32 s99, s99, 0
	v_lshl_add_u64 v[242:243], s[98:99], 0, v[98:99]
	s_add_u32 s98, s98, 0x2000
	s_addc_u32 s99, s99, 0
	v_lshl_add_u64 v[244:245], s[98:99], 0, v[98:99]
	s_sub_u32 s98, s98, 0xe000
	s_subb_u32 s99, s99, 0
	global_load_dword v246, v[242:243], off sc1
	global_load_dword v246, v[244:245], off sc1
	global_load_dword v246, v[200:201], off offset:896 sc1

	s_sub_u32 s98, s98, 0x3000
	s_subb_u32 s99, s99, 0

	s_waitcnt lgkmcnt(7)
	v_mfma_f32_32x32x16_bf16 v[32:47], v[176:179], v[108:111], v[32:47]
	v_add_f32_e32 v251, v87, v251
	v_cvt_pk_bf16_f32 v67, v70, v71
	v_exp_f32_e32 v89, v89
	v_add_f32_e32 v251, v88, v251
	v_mfma_f32_32x32x16_bf16 v[48:63], v[140:143], v[112:115], v[48:63]
	v_exp_f32_e32 v90, v90
	v_add_f32_e32 v251, v89, v251
	v_cvt_pk_bf16_f32 v68, v72, v73
	v_exp_f32_e32 v91, v91
	s_waitcnt lgkmcnt(6)
	v_mfma_f32_32x32x16_bf16 v[32:47], v[160:163], v[112:115], v[32:47]
	v_add_f32_e32 v251, v90, v251
	v_exp_f32_e32 v92, v92
	v_add_f32_e32 v251, v91, v251
	v_cvt_pk_bf16_f32 v69, v74, v75
	s_waitcnt lgkmcnt(5)
	v_mfma_f32_32x32x16_bf16 v[48:63], v[148:151], v[116:119], v[48:63]
	v_exp_f32_e32 v93, v93
	v_add_f32_e32 v251, v92, v251
	v_exp_f32_e32 v94, v94
	v_add_f32_e32 v251, v93, v251
	v_add_u32_e32 v196, v208, v184
	ds_read_b128 v[212:215], v196 offset:53760
	ds_read_b128 v[216:219], v196 offset:49152
	ds_read_b128 v[220:223], v196 offset:49184
	ds_read_b128 v[224:227], v196 offset:53792
	ds_read_b128 v[228:231], v196 offset:49216
	ds_read_b128 v[232:235], v196 offset:53824
	ds_read_b128 v[236:239], v196 offset:49248
	ds_read_b128 v[240:243], v196 offset:53856
	s_waitcnt lgkmcnt(11)
	v_mfma_f32_32x32x16_bf16 v[32:47], v[168:171], v[116:119], v[32:47]
	v_cvt_pk_bf16_f32 v70, v76, v77
	v_exp_f32_e32 v95, v95
	v_add_f32_e32 v251, v94, v251
	v_add_f32_e32 v251, v95, v251
	v_mfma_f32_32x32x16_bf16 v[48:63], v[136:139], v[120:123], v[48:63]
	v_cvt_pk_bf16_f32 v71, v78, v79
	v_cvt_pk_bf16_f32 v80, v80, v81
	v_cvt_pk_bf16_f32 v81, v82, v83
	v_cvt_pk_bf16_f32 v82, v84, v85
	v_cvt_pk_bf16_f32 v83, v86, v87
	v_cvt_pk_bf16_f32 v84, v88, v89
	s_waitcnt lgkmcnt(10)
	v_mfma_f32_32x32x16_bf16 v[32:47], v[144:147], v[120:123], v[32:47]
	v_cvt_pk_bf16_f32 v85, v90, v91
	v_cvt_pk_bf16_f32 v86, v92, v93
	v_cvt_pk_bf16_f32 v87, v94, v95
	v_add_f32_e32 v195, v195, v251
	v_add_f32_e32 v198, v198, v195
	s_add_i32 s40, s40, 2
	s_waitcnt lgkmcnt(0)
	s_barrier

	s_cmp_ge_u32 s40, s69
	s_cbranch_scc1 .LatB_yplain

	v_add_u32_e32 v197, s6, v209
	s_setprio 1
	v_mfma_f32_32x32x16_bf16 v[0:15], v[64:67], v[212:215], v[0:15]
	ds_read_b128 v[172:175], v197
	ds_read_b128 v[152:155], v197 offset:32
	v_mfma_f32_32x32x16_bf16 v[0:15], v[68:71], v[224:227], v[0:15]
	ds_read_b128 v[180:183], v197 offset:6656
	ds_read_b128 v[164:167], v197 offset:6688
	v_mfma_f32_32x32x16_bf16 v[0:15], v[80:83], v[232:235], v[0:15]
	ds_read_b128 v[156:159], v197 offset:64
	ds_read_b128 v[140:143], v197 offset:96
	v_exp_f32_e32 v48, v48
	v_exp_f32_e32 v49, v49
	v_exp_f32_e32 v50, v50
	v_add_f32_e32 v195, v48, v49
	v_mfma_f32_32x32x16_bf16 v[0:15], v[84:87], v[240:243], v[0:15]
	s_setprio 0
	ds_read_b128 v[176:179], v197 offset:6720
	ds_read_b128 v[160:163], v197 offset:6752
	v_exp_f32_e32 v51, v51
	v_add_f32_e32 v195, v50, v195
	v_exp_f32_e32 v52, v52
	v_add_f32_e32 v195, v51, v195
	v_exp_f32_e32 v53, v53
	v_add_f32_e32 v195, v52, v195
	v_mfma_f32_32x32x16_bf16 v[16:31], v[64:67], v[216:219], v[16:31]
	ds_read_b128 v[148:151], v197 offset:128
	ds_read_b128 v[136:139], v197 offset:160
	v_exp_f32_e32 v54, v54
	v_add_f32_e32 v195, v53, v195
	v_exp_f32_e32 v55, v55
	v_add_f32_e32 v195, v54, v195
	v_exp_f32_e32 v56, v56
	v_mfma_f32_32x32x16_bf16 v[16:31], v[68:71], v[220:223], v[16:31]
	ds_read_b128 v[168:171], v197 offset:6784
	ds_read_b128 v[144:147], v197 offset:6816
	v_add_f32_e32 v195, v55, v195
	v_exp_f32_e32 v57, v57
	v_add_f32_e32 v195, v56, v195
	v_exp_f32_e32 v58, v58
	v_add_f32_e32 v195, v57, v195
	v_mfma_f32_32x32x16_bf16 v[16:31], v[80:83], v[228:231], v[16:31]
	v_exp_f32_e32 v59, v59
	v_add_f32_e32 v195, v58, v195
	v_exp_f32_e32 v60, v60
	v_add_f32_e32 v195, v59, v195
	v_exp_f32_e32 v61, v61
	v_mfma_f32_32x32x16_bf16 v[16:31], v[84:87], v[236:239], v[16:31]
	v_add_f32_e32 v195, v60, v195
	v_exp_f32_e32 v62, v62
	v_add_f32_e32 v195, v61, v195
	v_exp_f32_e32 v63, v63
	v_add_f32_e32 v195, v62, v195
	v_add_f32_e32 v195, v63, v195
	s_branch .LatB_ctl
